# static s_setprio 1 for waves 4-7 (instead of per-tile alternation) in the attention tile loop and the SSD-out stage-3 loop; on top of v23
# baseline (speedup 1.0000x reference)
; __device__ __forceinline__ void attn_unit(Frame& F, const Ptrs& P, int u, int u_next, bf16x8 (&qa)[4], ScanRider& R) {
;     ...
;     for (int jj = 0; jj < (dry ? PROBE_ATT_TRIPS : 5); ++jj) {
;         const int j = jlo + jj;
;         if (wid >= 4) { if (jj & 1) __builtin_amdgcn_s_setprio(0); else __builtin_amdgcn_s_setprio(1); }
.LBB0_651:
	s_andn2_b64 vcc, exec, s[16:17]
	s_cbranch_vccnz .LBB0_656
	s_bitcmp0_b32 s82, 0
	s_mov_b64 s[4:5], -1
	s_cbranch_scc1 .LBB0_654
	s_setprio 1
	s_mov_b64 s[4:5], 0

; template <class Wait>
; __device__ __forceinline__ void out_unit(Frame& F, const Ptrs& P, int b, int c, int g, const Wait& wait) {
;     ...
; #pragma unroll 1
;         for (int ks = 0; ks < 8; ++ks) {
;             if (wid >= 4) { if (ks & 1) __builtin_amdgcn_s_setprio(0); else __builtin_amdgcn_s_setprio(1); }
.LBB0_744:
	s_andn2_b64 vcc, exec, s[20:21]
	s_cbranch_vccnz .LBB0_749
	s_bitcmp0_b32 s4, 0
	s_mov_b64 s[0:1], -1
	s_cbranch_scc1 .LBB0_747
	s_setprio 1
	s_mov_b64 s[0:1], 0
